# attention loop hand-rescheduled + V^T workspace row stride padded (L2 channel spread)
# speedup vs baseline: 1.0358x; 1.0040x over previous
.LBB0_1236:
	s_add_u32 s8, s46, 0x1ac00000
	s_addc_u32 s9, s47, 0
	s_lshl_b32 s1, s1, 5
	s_mov_b64 s[10:11], 0x80
	s_and_b32 s1, s1, 0x60
	s_add_i32 m0, s27, 0x18000
	v_lshl_add_u64 v[6:7], v[6:7], 0, s[10:11]
	s_lshl_b32 s16, s13, 13
	s_lshl_b32 s17, s1, 7
	s_waitcnt vmcnt(2)
	s_barrier
	global_load_lds_dwordx4 v[6:7], off
	v_lshl_add_u64 v[4:5], v[4:5], 0, s[10:11]
	s_add_i32 m0, s27, 0x1a000
	s_add_i32 s77, s27, 0x8000
	s_add_i32 s79, s27, 0xa000
	global_load_lds_dwordx4 v[4:5], off
	v_lshl_add_u64 v[0:1], v[0:1], 0, s[10:11]
	s_mov_b32 m0, s77
	s_add_u32 s14, s28, 0x10080
	global_load_lds_dwordx4 v[0:1], off
	v_lshl_add_u64 v[0:1], v[2:3], 0, s[10:11]
	s_mov_b32 m0, s79
	s_addc_u32 s15, s29, 0
	global_load_lds_dwordx4 v[0:1], off
	s_add_i32 m0, s27, 0x1c000
	v_lshl_add_u64 v[0:1], s[14:15], 0, v[130:131]
	global_load_lds_dwordx4 v[0:1], off
	v_lshl_add_u64 v[0:1], s[14:15], 0, v[134:135]
	s_add_i32 m0, s27, 0x1e000
	s_cmpk_lt_u32 s12, 0x100
	global_load_lds_dwordx4 v[0:1], off
	v_lshrrev_b32_e32 v1, 1, v8
	v_and_b32_e32 v1, 24, v1
	v_and_b32_e32 v0, 15, v8
	v_lshlrev_b32_e32 v2, 1, v1
	v_lshl_or_b32 v142, s13, 6, v0
	v_lshl_or_b32 v0, v0, 6, v2
	v_lshlrev_b32_e32 v2, 2, v8
	v_and_b32_e32 v2, 32, v2
	s_waitcnt vmcnt(6)
	v_bitop3_b32 v3, v0, s16, v2 bitop3:0xde
	v_bitop3_b32 v143, v0, s17, v2 bitop3:0xde
	s_cselect_b64 s[12:13], -1, 0
	s_add_i32 s81, 0, 0x10000
	s_add_i32 s82, 0, 0x14000
	s_sext_i32_i16 s54, s0
	s_ashr_i32 s80, s3, 31
	v_or_b32_e32 v144, s1, v1
	v_mov_b64_e32 v[136:137], 0x200
	v_mov_b64_e32 v[138:139], 0x1ff
	v_add_u32_e32 v145, s81, v143
	v_add_u32_e32 v146, s82, v143
	v_add_u32_e32 v147, 0, v3
	s_mov_b32 s83, 0x990000
	s_mov_b64 s[14:15], 0xaa0000
	s_mov_b32 s84, 0xaa0000
	s_mov_b64 s[16:17], 0xbb0000
	s_mov_b32 s85, 0xbb0000
	s_barrier
	s_branch .LBB0_1239

.LBB0_1249:
	v_lshl_add_u32 v148, s26, 8, v142
	v_lshl_or_b32 v140, s54, 8, v144
	v_ashrrev_i32_e32 v149, 31, v148
	v_ashrrev_i32_e32 v141, 31, v140
	v_mul_u32_u24_e32 v150, 0x11000, v148
	v_mov_b32_e32 v151, 0
	v_lshl_add_u64 v[150:151], s[8:9], 0, v[150:151]
	v_lshlrev_b64 v[152:153], 1, v[140:141]
	v_lshl_add_u64 v[140:141], v[150:151], 0, v[152:153]
	v_cvt_pk_bf16_f32 v124, v124, v125
	v_cvt_pk_bf16_f32 v125, v126, v127
	v_cvt_pk_bf16_f32 v126, v120, v121
	v_cvt_pk_bf16_f32 v127, v122, v123
	global_store_dwordx4 v[140:141], v[124:127], off
	v_cvt_pk_bf16_f32 v112, v112, v113
	v_cvt_pk_bf16_f32 v113, v114, v115
	v_cvt_pk_bf16_f32 v114, v104, v105
	v_or_b32_e32 v104, 16, v148
	v_ashrrev_i32_e32 v105, 31, v104
	v_mul_u32_u24_e32 v104, 0x11000, v104
	v_lshl_add_u64 v[104:105], s[8:9], 0, v[104:105]
	v_cvt_pk_bf16_f32 v115, v106, v107
	global_store_dwordx4 v[140:141], v[112:115], off offset:256
	s_mov_b32 s19, 0x880000
	s_mov_b64 s[28:29], 0x880000
	v_lshl_add_u64 v[112:113], v[104:105], 0, v[152:153]
	v_cvt_pk_bf16_f32 v104, v116, v117
	v_cvt_pk_bf16_f32 v105, v118, v119
	v_cvt_pk_bf16_f32 v106, v108, v109
	v_cvt_pk_bf16_f32 v107, v110, v111
	global_store_dwordx4 v[112:113], v[104:107], off
	v_cvt_pk_bf16_f32 v96, v96, v97
	v_cvt_pk_bf16_f32 v97, v98, v99
	v_cvt_pk_bf16_f32 v98, v88, v89
	v_or_b32_e32 v88, 32, v148
	v_ashrrev_i32_e32 v89, 31, v88
	v_mul_u32_u24_e32 v88, 0x11000, v88
	v_lshl_add_u64 v[88:89], s[8:9], 0, v[88:89]
	v_cvt_pk_bf16_f32 v99, v90, v91
	global_store_dwordx4 v[112:113], v[96:99], off offset:256
	s_nop 1
	v_lshl_add_u64 v[96:97], v[88:89], 0, v[152:153]
	v_cvt_pk_bf16_f32 v88, v100, v101
	v_cvt_pk_bf16_f32 v89, v102, v103
	v_cvt_pk_bf16_f32 v90, v92, v93
	v_cvt_pk_bf16_f32 v91, v94, v95
	global_store_dwordx4 v[96:97], v[88:91], off
	v_cvt_pk_bf16_f32 v80, v80, v81
	v_cvt_pk_bf16_f32 v81, v82, v83
	v_cvt_pk_bf16_f32 v82, v72, v73
	v_or_b32_e32 v72, 48, v148
	v_ashrrev_i32_e32 v73, 31, v72
	v_mul_u32_u24_e32 v72, 0x11000, v72
	v_lshl_add_u64 v[72:73], s[8:9], 0, v[72:73]
	v_cvt_pk_bf16_f32 v83, v74, v75
	global_store_dwordx4 v[96:97], v[80:83], off offset:256
	s_nop 1
	v_lshl_add_u64 v[80:81], v[72:73], 0, v[152:153]
	v_cvt_pk_bf16_f32 v72, v84, v85
	v_cvt_pk_bf16_f32 v73, v86, v87
	v_cvt_pk_bf16_f32 v74, v76, v77
	v_cvt_pk_bf16_f32 v75, v78, v79
	global_store_dwordx4 v[80:81], v[72:75], off
	v_cvt_pk_bf16_f32 v68, v68, v69
	v_cvt_pk_bf16_f32 v69, v70, v71
	v_cvt_pk_bf16_f32 v70, v64, v65
	v_cvt_pk_bf16_f32 v71, v66, v67
	global_store_dwordx4 v[80:81], v[68:71], off offset:256
	v_cvt_pk_bf16_f32 v60, v60, v61
	v_cvt_pk_bf16_f32 v61, v62, v63
	v_cvt_pk_bf16_f32 v62, v56, v57
	v_add_co_u32_e32 v56, vcc, s19, v140
	v_lshl_add_u64 v[64:65], v[140:141], 0, s[28:29]
	s_nop 0
	v_addc_co_u32_e32 v57, vcc, 0, v141, vcc
	v_cvt_pk_bf16_f32 v63, v58, v59
	global_store_dwordx4 v[56:57], v[60:63], off
	v_cvt_pk_bf16_f32 v48, v48, v49
	v_cvt_pk_bf16_f32 v49, v50, v51
	v_cvt_pk_bf16_f32 v50, v40, v41
	v_cvt_pk_bf16_f32 v51, v42, v43
	global_store_dwordx4 v[64:65], v[48:51], off offset:256
	s_mov_b64 s[28:29], 0x990000
	v_cvt_pk_bf16_f32 v40, v52, v53
	v_cvt_pk_bf16_f32 v41, v54, v55
	v_cvt_pk_bf16_f32 v42, v44, v45
	v_add_co_u32_e32 v44, vcc, s83, v140
	v_lshl_add_u64 v[48:49], v[140:141], 0, s[28:29]
	s_nop 0
	v_addc_co_u32_e32 v45, vcc, 0, v141, vcc
	v_cvt_pk_bf16_f32 v43, v46, v47
	global_store_dwordx4 v[44:45], v[40:43], off
	v_cvt_pk_bf16_f32 v32, v32, v33
	v_cvt_pk_bf16_f32 v33, v34, v35
	v_cvt_pk_bf16_f32 v34, v24, v25
	v_cvt_pk_bf16_f32 v35, v26, v27
	global_store_dwordx4 v[48:49], v[32:35], off offset:256
	v_cvt_pk_bf16_f32 v24, v36, v37
	v_cvt_pk_bf16_f32 v25, v38, v39
	v_cvt_pk_bf16_f32 v26, v28, v29
	v_add_co_u32_e32 v28, vcc, s84, v140
	s_nop 0
	v_lshl_add_u64 v[32:33], v[140:141], 0, s[14:15]
	v_addc_co_u32_e32 v29, vcc, 0, v141, vcc
	v_cvt_pk_bf16_f32 v27, v30, v31
	global_store_dwordx4 v[28:29], v[24:27], off
	v_cvt_pk_bf16_f32 v16, v16, v17
	v_cvt_pk_bf16_f32 v17, v18, v19
	v_cvt_pk_bf16_f32 v18, v8, v9
	v_cvt_pk_bf16_f32 v19, v10, v11
	global_store_dwordx4 v[32:33], v[16:19], off offset:256
	v_cvt_pk_bf16_f32 v8, v20, v21
	v_cvt_pk_bf16_f32 v9, v22, v23
	v_cvt_pk_bf16_f32 v10, v12, v13
	v_add_co_u32_e32 v12, vcc, s85, v140
	s_nop 0
	v_lshl_add_u64 v[16:17], v[140:141], 0, s[16:17]
	v_addc_co_u32_e32 v13, vcc, 0, v141, vcc
	s_andn2_b64 vcc, exec, s[0:1]
	s_mov_b64 s[0:1], -1
	v_cvt_pk_bf16_f32 v11, v14, v15
	global_store_dwordx4 v[12:13], v[8:11], off
	v_cvt_pk_bf16_f32 v4, v4, v5
	v_cvt_pk_bf16_f32 v5, v6, v7
	v_cvt_pk_bf16_f32 v6, v0, v1
	v_cvt_pk_bf16_f32 v7, v2, v3
	global_store_dwordx4 v[16:17], v[4:7], off offset:256
	s_cbranch_vccnz .LBB0_1238
	s_andn2_b64 vcc, exec, s[4:5]
	s_cbranch_vccnz .LBB0_1237
	s_barrier
	s_branch .LBB0_1237

.LBB0_1338:
	v_mov_b32_e32 v54, v191
	s_lshl_b32 s97, s4, 8
	s_add_i32 s97, s97, s79
	v_and_b32_e32 v48, 31, v54
	v_or_b32_e32 v0, s97, v48
	v_ashrrev_i32_e32 v50, 3, v54
	v_and_b32_e32 v56, 7, v54
	v_bfe_u32 v49, v54, 5, 1
	v_add_u32_e32 v0, s91, v0
	s_movk_i32 s0, 0xc00
	v_ashrrev_i32_e32 v51, 4, v54
	v_and_b32_e32 v55, 15, v54
	v_add_u32_e32 v9, s91, v50
	v_lshlrev_b32_e32 v52, 3, v56
	v_ashrrev_i32_e32 v1, 31, v0
	v_mad_i64_i32 v[2:3], s[0:1], v0, s0, v[182:183]
	v_lshlrev_b32_e32 v180, 4, v49
	v_add_lshl_u32 v8, v51, s91, 10
	v_lshlrev_b32_e32 v53, 3, v55
	v_lshl_or_b32 v10, v9, 6, v52
	v_add_lshl_u32 v9, v50, s92, 15
	v_lshl_add_u64 v[24:25], v[2:3], 0, v[180:181]
	v_lshlrev_b64 v[0:1], 7, v[0:1]
	v_or3_b32 v8, v8, v53, s92
	v_or3_b32 v12, v9, s91, v52
	v_add_lshl_u32 v234, v50, s92, 11
	v_add_u32_e32 v12, v12, v234
	v_mov_b32_e32 v9, v181
	global_load_dwordx4 v[96:99], v[24:25], off
	global_load_dwordx4 v[100:103], v[24:25], off offset:32
	global_load_dwordx4 v[104:107], v[24:25], off offset:64
	global_load_dwordx4 v[108:111], v[24:25], off offset:96
	global_load_dwordx4 v[112:115], v[24:25], off offset:128
	global_load_dwordx4 v[116:119], v[24:25], off offset:160
	global_load_dwordx4 v[120:123], v[24:25], off offset:192
	global_load_dwordx4 v[124:127], v[24:25], off offset:224
	v_lshl_add_u64 v[2:3], s[62:63], 0, v[0:1]
	v_lshlrev_b32_e32 v4, 5, v49
	v_mov_b32_e32 v5, v181
	v_lshl_add_u64 v[14:15], v[8:9], 1, s[64:65]
	v_add_u32_e32 v8, 0x8000, v8
	v_lshl_add_u64 v[28:29], v[2:3], 0, v[4:5]
	v_lshl_add_u64 v[0:1], s[66:67], 0, v[0:1]
	v_lshl_add_u64 v[8:9], v[8:9], 1, s[64:65]
	v_mov_b32_e32 v11, v181
	v_lshl_add_u64 v[44:45], v[0:1], 0, v[4:5]
	global_load_dwordx4 v[0:3], v[28:29], off offset:16
	global_load_dwordx4 v[4:7], v[28:29], off
	global_load_dwordx4 v[128:131], v[14:15], off
	global_load_dwordx4 v[132:135], v[8:9], off
	v_lshl_add_u64 v[8:9], v[10:11], 1, s[60:61]
	v_mov_b32_e32 v13, v181
	v_lshl_add_u64 v[10:11], v[12:13], 1, s[68:69]
	global_load_dwordx4 v[136:139], v[8:9], off
	global_load_dwordx4 v[140:143], v[10:11], off
	v_add_u32_e32 v8, 0x220000, v12
	v_mov_b32_e32 v9, v181
	v_lshl_add_u64 v[8:9], v[8:9], 1, s[68:69]
	global_load_dwordx4 v[144:147], v[8:9], off
	s_nop 0
	global_load_dwordx4 v[8:11], v[44:45], off offset:16
	global_load_dwordx4 v[20:23], v[44:45], off
	global_load_dwordx4 v[12:15], v[24:25], off offset:256
	global_load_dwordx4 v[32:35], v[24:25], off offset:288
	global_load_dwordx4 v[16:19], v[24:25], off offset:320
	global_load_dwordx4 v[36:39], v[24:25], off offset:352
	s_nop 0
	global_load_dwordx4 v[24:27], v[28:29], off offset:80
	global_load_dwordx4 v[40:43], v[28:29], off offset:64
	s_nop 0
	global_load_dwordx4 v[28:31], v[44:45], off offset:80
	s_nop 0
	global_load_dwordx4 v[44:47], v[44:45], off offset:64
	v_lshlrev_b32_e32 v57, 3, v54
	v_mul_lo_u32 v58, v51, s82
	v_lshlrev_b32_e32 v54, 4, v56
	v_mul_lo_u32 v56, v50, s83
	v_lshl_add_u32 v194, v55, 4, v58
	v_and_b32_e32 v55, 0x60, v54
	v_and_b32_e32 v57, 8, v57
	v_mad_u64_u32 v[184:185], s[0:1], v50, s82, v[54:55]
	v_add_u32_e32 v54, 0, v56
	v_add3_u32 v185, v54, v57, v55
	v_add_u32_e32 v56, 0, v194
	v_add_u32_e32 v54, 0xc800, v185
	v_add_u32_e32 v58, 0, v184
	v_add_u32_e32 v55, 0xe800, v185
	s_cmp_lt_i32 s4, 0
	s_mov_b32 s52, 0
	s_waitcnt vmcnt(0)
	ds_write_b128 v56, v[128:131]
	ds_write_b128 v56, v[132:135] offset:12800
	ds_write_b128 v58, v[136:139] offset:256
	ds_write2_b64 v54, v[140:141], v[142:143] offset1:2
	ds_write2_b64 v55, v[144:145], v[146:147] offset0:128 offset1:130
	v_mad_u32_u24 v54, v48, s83, 0
	v_add_u32_e32 v195, v54, v180
	v_add_u32_e32 v173, 0xc800, v195
	s_waitcnt lgkmcnt(0)
	s_barrier
	s_cbranch_scc1 .LBB0_1331
	v_lshlrev_b32_e32 v55, 8, v48
	v_add3_u32 v196, v54, v55, v180
	v_and_b32_e32 v55, 0xffff0000, v36
	v_lshlrev_b32_e32 v54, 16, v36
	v_and_b32_e32 v57, 0xffff0000, v32
	v_lshlrev_b32_e32 v56, 16, v32
	v_pk_mul_f32 v[58:59], v[44:45], v[56:57]
	v_pk_mul_f32 v[44:45], v[44:45], v[54:55]
	v_pk_fma_f32 v[58:59], v[40:41], v[54:55], v[58:59]
	v_pk_fma_f32 v[40:41], v[40:41], v[56:57], v[44:45] neg_lo:[0,0,1] neg_hi:[0,0,1]
	v_lshlrev_b32_e32 v36, 16, v33
	v_cvt_pk_bf16_f32 v152, v40, v41
	v_and_b32_e32 v41, 0xffff0000, v37
	v_lshlrev_b32_e32 v40, 16, v37
	v_and_b32_e32 v37, 0xffff0000, v33
	v_pk_mul_f32 v[32:33], v[46:47], v[36:37]
	s_lshl_b32 s53, s4, 2
	v_pk_fma_f32 v[32:33], v[42:43], v[40:41], v[32:33]
	v_mov_b32_e32 v200, 0
	v_cvt_pk_bf16_f32 v149, v32, v33
	v_pk_mul_f32 v[32:33], v[46:47], v[40:41]
	s_add_i32 s53, s53, 4
	v_pk_fma_f32 v[32:33], v[42:43], v[36:37], v[32:33] neg_lo:[0,0,1] neg_hi:[0,0,1]
	v_and_b32_e32 v37, 0xffff0000, v34
	v_cvt_pk_bf16_f32 v153, v32, v33
	v_and_b32_e32 v33, 0xffff0000, v38
	v_lshlrev_b32_e32 v32, 16, v38
	v_lshlrev_b32_e32 v36, 16, v34
	v_pk_mul_f32 v[40:41], v[28:29], v[36:37]
	v_pk_mul_f32 v[28:29], v[28:29], v[32:33]
	v_pk_fma_f32 v[40:41], v[24:25], v[32:33], v[40:41]
	v_pk_fma_f32 v[24:25], v[24:25], v[36:37], v[28:29] neg_lo:[0,0,1] neg_hi:[0,0,1]
	v_and_b32_e32 v29, 0xffff0000, v35
	v_lshlrev_b32_e32 v28, 16, v35
	v_cvt_pk_bf16_f32 v154, v24, v25
	v_and_b32_e32 v25, 0xffff0000, v39
	v_lshlrev_b32_e32 v24, 16, v39
	v_pk_mul_f32 v[32:33], v[30:31], v[28:29]
	v_cvt_pk_bf16_f32 v148, v58, v59
	v_pk_fma_f32 v[32:33], v[26:27], v[24:25], v[32:33]
	v_pk_mul_f32 v[24:25], v[30:31], v[24:25]
	v_cvt_pk_bf16_f32 v150, v40, v41
	v_pk_fma_f32 v[24:25], v[26:27], v[28:29], v[24:25] neg_lo:[0,0,1] neg_hi:[0,0,1]
	v_and_b32_e32 v27, 0xffff0000, v12
	v_cvt_pk_bf16_f32 v155, v24, v25
	v_and_b32_e32 v25, 0xffff0000, v16
	v_lshlrev_b32_e32 v24, 16, v16
	v_lshlrev_b32_e32 v26, 16, v12
	v_pk_mul_f32 v[28:29], v[20:21], v[26:27]
	v_pk_mul_f32 v[20:21], v[20:21], v[24:25]
	v_pk_fma_f32 v[28:29], v[4:5], v[24:25], v[28:29]
	v_pk_fma_f32 v[4:5], v[4:5], v[26:27], v[20:21] neg_lo:[0,0,1] neg_hi:[0,0,1]
	v_lshlrev_b32_e32 v16, 16, v13
	v_cvt_pk_bf16_f32 v160, v4, v5
	v_and_b32_e32 v5, 0xffff0000, v17
	v_lshlrev_b32_e32 v4, 16, v17
	v_and_b32_e32 v17, 0xffff0000, v13
	v_pk_mul_f32 v[12:13], v[22:23], v[16:17]
	v_cvt_pk_bf16_f32 v151, v32, v33
	v_pk_fma_f32 v[12:13], v[6:7], v[4:5], v[12:13]
	v_pk_mul_f32 v[4:5], v[22:23], v[4:5]
	v_cvt_pk_bf16_f32 v157, v12, v13
	v_pk_fma_f32 v[4:5], v[6:7], v[16:17], v[4:5] neg_lo:[0,0,1] neg_hi:[0,0,1]
	v_and_b32_e32 v7, 0xffff0000, v14
	v_lshlrev_b32_e32 v6, 16, v14
	v_cvt_pk_bf16_f32 v161, v4, v5
	v_and_b32_e32 v5, 0xffff0000, v18
	v_lshlrev_b32_e32 v4, 16, v18
	v_pk_mul_f32 v[12:13], v[8:9], v[6:7]
	v_cvt_pk_bf16_f32 v156, v28, v29
	v_pk_fma_f32 v[12:13], v[0:1], v[4:5], v[12:13]
	v_pk_mul_f32 v[4:5], v[8:9], v[4:5]
	v_cvt_pk_bf16_f32 v158, v12, v13
	v_pk_fma_f32 v[0:1], v[0:1], v[6:7], v[4:5] neg_lo:[0,0,1] neg_hi:[0,0,1]
	v_and_b32_e32 v5, 0xffff0000, v15
	v_lshlrev_b32_e32 v4, 16, v15
	v_cvt_pk_bf16_f32 v162, v0, v1
	v_and_b32_e32 v1, 0xffff0000, v19
	v_lshlrev_b32_e32 v0, 16, v19
	v_pk_mul_f32 v[6:7], v[10:11], v[4:5]
	v_mov_b32_e32 v199, 0xf149f2ca
	v_pk_fma_f32 v[6:7], v[2:3], v[0:1], v[6:7]
	v_pk_mul_f32 v[0:1], v[10:11], v[0:1]
	v_cvt_pk_bf16_f32 v159, v6, v7
	v_pk_fma_f32 v[0:1], v[2:3], v[4:5], v[0:1] neg_lo:[0,0,1] neg_hi:[0,0,1]
	s_mov_b32 s33, 63
	v_cvt_pk_bf16_f32 v163, v0, v1
	v_lshlrev_b32_e32 v1, 10, v51
	v_lshlrev_b32_e32 v0, 2, v49
	v_add3_u32 v186, s93, v1, v53
	v_add_u32_e32 v1, s97, v48
	v_sub_u32_e32 v197, v1, v0
	v_lshlrev_b32_e32 v0, 6, v50
	v_add3_u32 v188, s94, v0, v52
	v_lshlrev_b32_e32 v0, 15, v50
	v_add3_u32 v198, s95, v0, v52
	v_add_lshl_u32 v234, v50, s92, 11
	v_add_u32_e32 v198, v198, v234
	v_mov_b32_e32 v64, 0
	v_mov_b32_e32 v65, 0
	v_mov_b32_e32 v66, 0
	v_mov_b32_e32 v67, 0
	v_mov_b32_e32 v68, 0
	v_mov_b32_e32 v69, 0
	v_mov_b32_e32 v70, 0
	v_mov_b32_e32 v71, 0
	s_mov_b32 s0, 0
	v_mov_b32_e32 v0, 0
	v_mov_b32_e32 v1, v200
	v_mov_b32_e32 v2, v200
	v_mov_b32_e32 v3, v200
	v_mov_b32_e32 v4, v200
	v_mov_b32_e32 v5, v200
	v_mov_b32_e32 v6, v200
	v_mov_b32_e32 v7, v200
	v_mov_b32_e32 v8, v200
	v_mov_b32_e32 v9, v200
	v_mov_b32_e32 v10, v200
	v_mov_b32_e32 v11, v200
	v_mov_b32_e32 v12, v200
	v_mov_b32_e32 v13, v200
	v_mov_b32_e32 v14, v200
	v_mov_b32_e32 v15, v200
	v_mov_b32_e32 v16, 0
	v_mov_b32_e32 v17, v200
	v_mov_b32_e32 v18, v200
	v_mov_b32_e32 v19, v200
	v_mov_b32_e32 v20, v200
	v_mov_b32_e32 v21, v200
	v_mov_b32_e32 v22, v200
	v_mov_b32_e32 v23, v200
	v_mov_b32_e32 v24, v200
	v_mov_b32_e32 v25, v200
	v_mov_b32_e32 v26, v200
	v_mov_b32_e32 v27, v200
	v_mov_b32_e32 v28, v200
	v_mov_b32_e32 v29, v200
	v_mov_b32_e32 v30, v200
	v_mov_b32_e32 v31, v200
	v_mov_b32_e32 v32, 0
	v_mov_b32_e32 v33, v200
	v_mov_b32_e32 v34, v200
	v_mov_b32_e32 v35, v200
	v_mov_b32_e32 v36, v200
	v_mov_b32_e32 v37, v200
	v_mov_b32_e32 v38, v200
	v_mov_b32_e32 v39, v200
	v_mov_b32_e32 v40, v200
	v_mov_b32_e32 v41, v200
	v_mov_b32_e32 v42, v200
	v_mov_b32_e32 v43, v200
	v_mov_b32_e32 v44, v200
	v_mov_b32_e32 v45, v200
	v_mov_b32_e32 v46, v200
	v_mov_b32_e32 v47, v200
	v_mov_b32_e32 v48, 0
	v_mov_b32_e32 v49, v200
	v_mov_b32_e32 v50, v200
	v_mov_b32_e32 v51, v200
	v_mov_b32_e32 v52, v200
	v_mov_b32_e32 v53, v200
	v_mov_b32_e32 v54, v200
	v_mov_b32_e32 v55, v200
	v_mov_b32_e32 v56, v200
	v_mov_b32_e32 v57, v200
	v_mov_b32_e32 v58, v200
	v_mov_b32_e32 v59, v200
	v_mov_b32_e32 v60, v200
	v_mov_b32_e32 v61, v200
	v_mov_b32_e32 v62, v200
	v_mov_b32_e32 v63, v200
	v_mov_b32_e32 v187, 0
	v_mov_b32_e32 v189, 0
	v_xor_b32_e32 v246, 32, v193
	v_lshlrev_b32_e32 v246, 2, v246
	v_mov_b32_e32 v64, 0xff61b1e6
	v_mov_b32_e32 v65, v64
	v_mov_b32_e32 v66, v64
	v_mov_b32_e32 v67, v64
	v_mov_b32_e32 v68, v64
	v_mov_b32_e32 v69, v64
	v_mov_b32_e32 v70, v64
	v_mov_b32_e32 v71, v64
	v_mov_b32_e32 v72, v64
	v_mov_b32_e32 v73, v64
	v_mov_b32_e32 v74, v64
	v_mov_b32_e32 v75, v64
	v_mov_b32_e32 v76, v64
	v_mov_b32_e32 v77, v64
	v_mov_b32_e32 v78, v64
	v_mov_b32_e32 v79, v64
	v_add_u32_e32 v180, 0xffff8000, v186
	v_lshl_add_u64 v[244:245], v[180:181], 1, s[64:65]
	global_load_dwordx4 v[128:131], v[244:245], off
	v_lshl_add_u64 v[244:245], v[186:187], 1, s[64:65]
	global_load_dwordx4 v[132:135], v[244:245], off
	v_lshl_add_u64 v[244:245], v[188:189], 1, s[60:61]
	global_load_dwordx4 v[136:139], v[244:245], off
	v_add_u32_e32 v235, s33, v198
	v_add_u32_e32 v180, 1, v235
	v_lshl_add_u64 v[244:245], v[180:181], 1, s[68:69]
	global_load_dwordx4 v[140:143], v[244:245], off
	v_add_u32_e32 v180, 0x220001, v235
	v_lshl_add_u64 v[244:245], v[180:181], 1, s[68:69]
	global_load_dwordx4 v[144:147], v[244:245], off

.Lat_skip_st:
	s_add_i32 s4, s54, 1
	s_cmp_lt_i32 s4, s53
	s_cbranch_scc0 .Lat_skip_ld
	v_add_u32_e32 v186, 0x10000, v186
	v_add_u32_e32 v188, 0x1000, v188
	v_add_u32_e32 v180, 0xffff8000, v186
	v_lshl_add_u64 v[244:245], v[180:181], 1, s[64:65]
	global_load_dwordx4 v[128:131], v[244:245], off
	v_lshl_add_u64 v[244:245], v[186:187], 1, s[64:65]
	global_load_dwordx4 v[132:135], v[244:245], off
	v_lshl_add_u64 v[244:245], v[188:189], 1, s[60:61]
	global_load_dwordx4 v[136:139], v[244:245], off
	v_add_u32_e32 v235, s33, v198
	v_add_u32_e32 v180, 65, v235
	v_lshl_add_u64 v[244:245], v[180:181], 1, s[68:69]
	global_load_dwordx4 v[140:143], v[244:245], off
	v_add_u32_e32 v180, 0x220041, v235
	v_lshl_add_u64 v[244:245], v[180:181], 1, s[68:69]
	global_load_dwordx4 v[144:147], v[244:245], off
